# attention: static s_setprio 1 for waves 0-3 (older half) for the whole phase, s_setprio 0 at phase end (on v31)
# speedup vs baseline: 1.0070x; 1.0006x over previous
; #define LAS __attribute__((address_space(3)))
; __device__ __forceinline__ int lane_id_asm() { int l; asm volatile("v_mbcnt_lo_u32_b32 %0, -1, 0\n\tv_mbcnt_hi_u32_b32 %0, -1, %0" : "=v"(l)); return l; }
; __device__ __forceinline__ void att_mfma(const Params& P, LAS unsigned char* lds, int wave) {
;     unsigned char* ws = P.ws;
;     const bf16_t* Q = (const bf16_t*)(ws + WS_R + R_Q); const bf16_t* KV = (const bf16_t*)(ws + WS_R + R_KV); bf16_t* O = (bf16_t*)(ws + WS_R + R_O);
;     const int lane = lane_id_asm(), q32 = lane & 31, hf = lane >> 5;
;     constexpr int KP = 400, VP = 320, KB = 64 * KP, BUF = KB + 64 * VP;
;     unsigned goff[6];
; #pragma unroll
;     for (int i = 0; i < 6; ++i) { int q = wave + 8 * i; q = q > 44 ? 44 : q; int p = q * 64 + lane;
;         if (q < 25) { const int r = p / 25; int c = p % 25; c = c == 24 ? 0 : c; goff[i] = (unsigned)(r * 5120 + c * 16); }
;         else { p -= 1600; const int r = p / 20; int c = p % 20; c = c >= 16 ? 0 : c; goff[i] = (unsigned)(r * 5120 + 384 + c * 16); } }
;     ...
;     const int i16 = lane & 15, blk = (lane >> 4) & 1;
;     const int vlane = KB + ((i16 >> 2) + 4 * hf) * VP + (16 * blk + 4 * (i16 & 3)) * 2;
;     const int klane = q32 * KP + hf * 16;
;     const bool roleA = wave < 4;
;     const int w4 = wave & 3;
.LBB0_1005:
	v_readlane_b32 s0, v254, 6
	v_readlane_b32 s1, v254, 7
	s_and_b64 vcc, exec, s[0:1]
	s_cbranch_vccz .LBB0_1028
	v_ashrrev_i32_e32 v1, 5, v0
	v_lshrrev_b32_e32 v3, 2, v0
	v_lshlrev_b32_e32 v152, 2, v1
	v_and_or_b32 v3, v3, 3, v152
	s_movk_i32 s0, 0x140
	s_cmpk_gt_u32 s3, 0xff
	v_mul_lo_u32 v3, v3, s0
	s_cselect_b64 s[0:1], -1, 0
	s_min_i32 s8, s33, 4
	v_and_b32_e32 v2, 16, v0
	v_lshlrev_b32_e32 v4, 2, v0
	s_or_b32 s11, s8, 40
	v_and_or_b32 v2, v4, 12, v2
	s_lshl_b32 s8, s11, 6
	v_lshlrev_b32_e32 v2, 1, v2
	s_addk_i32 s8, 0xf9c0
	v_add3_u32 v222, 0, v3, v2
	v_add_u32_e32 v2, s8, v0
	s_mov_b32 s8, 0x66666667
	v_mul_hi_i32 v3, v2, s8
	v_lshrrev_b32_e32 v5, 31, v3
	v_ashrrev_i32_e32 v3, 3, v3
	v_add_u32_e32 v3, v3, v5
	s_movk_i32 s9, 0x1400
	s_min_i32 s17, s33, 12
	v_mul_lo_u32 v5, v3, s9
	v_mul_lo_u32 v3, v3, 20
	s_or_b32 s17, s17, 32
	v_sub_u32_e32 v2, v2, v3
	s_lshl_b32 s19, s17, 6
	v_lshlrev_b32_e32 v3, 4, v2
	v_cmp_gt_i32_e32 vcc, 16, v2
	s_addk_i32 s19, 0xf9c0
	v_and_b32_e32 v4, 31, v0
	v_cndmask_b32_e32 v2, 0, v3, vcc
	s_movk_i32 s16, 0x180
	v_add_u32_e32 v0, s19, v0
	v_add3_u32 v154, v2, v5, s16
	v_mul_hi_i32 v2, v0, s8
	v_lshrrev_b32_e32 v3, 31, v2
	v_ashrrev_i32_e32 v2, 3, v2
	v_add_u32_e32 v2, v2, v3
	v_mul_lo_u32 v3, v2, s9
	v_mul_lo_u32 v2, v2, 20
	v_sub_u32_e32 v0, v0, v2
	v_lshlrev_b32_e32 v2, 4, v0
	v_cmp_gt_i32_e32 vcc, 16, v0
	v_lshlrev_b32_e32 v158, 3, v1
	s_bfe_u32 s18, s3, 0x20006
	v_cndmask_b32_e32 v0, 0, v2, vcc
	s_lshl_b32 s8, s33, 3
	v_ashrrev_i32_e32 v159, 31, v158
	v_add3_u32 v156, v0, v3, s16
	v_lshlrev_b32_e32 v5, 4, v1
	s_lshl_b32 s16, s18, 6
	s_and_b32 s25, s8, 0x1fffffe0
	v_lshlrev_b64 v[0:1], 2, v[158:159]
	v_lshl_add_u64 v[2:3], s[54:55], 0, v[0:1]
	s_mov_b64 s[8:9], 0xa02000
	s_cmp_eq_u32 s18, 3
	v_lshl_add_u64 v[160:161], v[2:3], 0, s[8:9]
	s_cselect_b64 s[8:9], -1, 0
	s_and_b64 s[8:9], s[0:1], s[8:9]
	s_lshl_b32 s19, s6, 10
	s_lshl_b32 s20, s4, 10
	s_lshl_b32 s21, s5, 10
	s_lshl_b32 s22, s10, 10
	s_lshl_b32 s23, s17, 10
	s_lshl_b32 s24, s11, 10
	s_add_i32 s16, s16, s25
	v_mul_u32_u24_e32 v6, 0x190, v4
	v_mov_b32_e32 v165, 0
	s_add_u32 s25, s54, 0x15050000
	s_mov_b32 s7, 0
	v_lshl_add_u64 v[162:163], s[60:61], 0, v[0:1]
	v_add3_u32 v223, 0, v6, v5
	v_ashrrev_i32_e32 v153, 31, v152
	v_mov_b32_e32 v145, v165
	v_mov_b32_e32 v147, v165
	v_mov_b32_e32 v149, v165
	v_mov_b32_e32 v151, v165
	v_mov_b32_e32 v157, v165
	v_mov_b32_e32 v155, v165
	v_or_b32_e32 v224, s16, v4
	s_addc_u32 s26, s55, 0
	s_add_i32 s27, s19, 0
	s_add_i32 s28, s20, 0
	s_add_i32 s29, s21, 0
	s_add_i32 s30, s22, 0
	s_add_i32 s31, s23, 0
	s_add_i32 s34, s24, 0
	s_movk_i32 s35, 0xc00
	v_mov_b64_e32 v[166:167], s[58:59]
	s_mov_b32 s36, 0x80000
	v_mov_b32_e32 v225, 0x358637bd
	s_mov_b32 s37, 0x41000000
	v_mbcnt_hi_u32_b32 v226, -1, v244
	s_mov_b32 s38, s2
	s_mov_b32 s39, s2
	s_cmp_lg_u64 s[0:1], 0
	s_cbranch_scc1 .Latt_noprio
	s_setprio 1
.Latt_noprio:
	s_branch .LBB0_1008
; __device__ __forceinline__ unsigned cvt_pk_bf16(float lo, float hi) { f32x2 v = {lo, hi}; bf16x2_t b = __builtin_convertvector(v, bf16x2_t); return __builtin_bit_cast(unsigned, b); }
; #define ATT_BAR() do { asm volatile("s_waitcnt vmcnt(0) lgkmcnt(0)" ::: "memory"); __builtin_amdgcn_s_barrier(); asm volatile("" ::: "memory"); } while (0)
; __device__ __forceinline__ void att_mfma(const Params& P, LAS unsigned char* lds, int wave) {
;     ...
;         ATT_BAR();
;         const float lt = lrun + __shfl_xor(lrun, 32), il = 1.f / lt;
;         bf16_t* op = O + qrow_g * 1024 + hh * 128 + 4 * hf;
; #pragma unroll
;         for (int d = 0; d < 4; ++d)
; #pragma unroll
;             for (int j = 0; j < 4; ++j) { u32x2 w; w.x = cvt_pk_bf16(o[d][4 * j] * il, o[d][4 * j + 1] * il); w.y = cvt_pk_bf16(o[d][4 * j + 2] * il, o[d][4 * j + 3] * il);
;                 *(u32x2*)(op + d * 32 + 8 * j) = w; }
;     }
.LBB0_1007:
	v_and_b32_e32 v65, 64, v226
	v_xor_b32_e32 v64, 32, v226
	v_add_u32_e32 v65, 64, v65
	v_cmp_lt_i32_e32 vcc, v64, v65
	s_lshl_b32 s6, s47, 8
	s_waitcnt vmcnt(0) lgkmcnt(0)
	s_barrier
	v_cndmask_b32_e32 v64, v226, v64, vcc
	v_lshlrev_b32_e32 v64, 2, v64
	ds_bpermute_b32 v64, v64, v168
	s_add_i32 s39, s39, s56
	s_add_i32 s73, s73, s46
	s_add_i32 s38, s38, s56
	s_waitcnt lgkmcnt(0)
	v_add_f32_e32 v64, v168, v64
	v_div_scale_f32 v65, s[4:5], v64, v64, 1.0
	v_rcp_f32_e32 v66, v65
	s_cmpk_lt_i32 s39, 0x400
	v_fma_f32 v67, -v65, v66, 1.0
	v_fmac_f32_e32 v66, v67, v66
	v_div_scale_f32 v67, vcc, 1.0, v64, 1.0
	v_mul_f32_e32 v68, v67, v66
	v_fma_f32 v69, -v65, v68, v67
	v_fmac_f32_e32 v68, v69, v66
	v_fma_f32 v65, -v65, v68, v67
	v_div_fmas_f32 v65, v65, v66, v68
	v_lshlrev_b64 v[66:67], 11, v[164:165]
	v_div_fixup_f32 v64, v65, v64, 1.0
	v_lshl_add_u64 v[66:67], s[44:45], 0, v[66:67]
	v_lshl_add_u64 v[66:67], v[66:67], 0, s[6:7]
	v_pk_mul_f32 v[48:49], v[48:49], v[64:65] op_sel_hi:[1,0]
	v_pk_mul_f32 v[50:51], v[50:51], v[64:65] op_sel_hi:[1,0]
	v_pk_mul_f32 v[32:33], v[32:33], v[64:65] op_sel_hi:[1,0]
	v_pk_mul_f32 v[34:35], v[34:35], v[64:65] op_sel_hi:[1,0]
	v_pk_mul_f32 v[16:17], v[16:17], v[64:65] op_sel_hi:[1,0]
	v_pk_mul_f32 v[18:19], v[18:19], v[64:65] op_sel_hi:[1,0]
	v_pk_mul_f32 v[0:1], v[0:1], v[64:65] op_sel_hi:[1,0]
	v_pk_mul_f32 v[2:3], v[2:3], v[64:65] op_sel_hi:[1,0]
	v_lshl_add_u64 v[66:67], v[152:153], 1, v[66:67]
	v_cvt_pk_bf16_f32 v48, v48, v49
	v_cvt_pk_bf16_f32 v49, v50, v51
	v_cvt_pk_bf16_f32 v32, v32, v33
	v_cvt_pk_bf16_f32 v33, v34, v35
	v_cvt_pk_bf16_f32 v16, v16, v17
	v_cvt_pk_bf16_f32 v17, v18, v19
	v_cvt_pk_bf16_f32 v0, v0, v1
	v_cvt_pk_bf16_f32 v1, v2, v3
	flat_store_dwordx2 v[66:67], v[48:49]
	v_pk_mul_f32 v[48:49], v[52:53], v[64:65] op_sel_hi:[1,0]
	v_pk_mul_f32 v[50:51], v[54:55], v[64:65] op_sel_hi:[1,0]
	flat_store_dwordx2 v[66:67], v[32:33] offset:64
	v_pk_mul_f32 v[32:33], v[36:37], v[64:65] op_sel_hi:[1,0]
	v_pk_mul_f32 v[34:35], v[38:39], v[64:65] op_sel_hi:[1,0]
	flat_store_dwordx2 v[66:67], v[16:17] offset:128
	v_pk_mul_f32 v[16:17], v[20:21], v[64:65] op_sel_hi:[1,0]
	v_pk_mul_f32 v[18:19], v[22:23], v[64:65] op_sel_hi:[1,0]
	flat_store_dwordx2 v[66:67], v[0:1] offset:192
	v_pk_mul_f32 v[0:1], v[4:5], v[64:65] op_sel_hi:[1,0]
	v_pk_mul_f32 v[2:3], v[6:7], v[64:65] op_sel_hi:[1,0]
	v_cvt_pk_bf16_f32 v48, v48, v49
	v_cvt_pk_bf16_f32 v49, v50, v51
	v_cvt_pk_bf16_f32 v32, v32, v33
	v_cvt_pk_bf16_f32 v33, v34, v35
	v_cvt_pk_bf16_f32 v16, v16, v17
	v_cvt_pk_bf16_f32 v17, v18, v19
	v_cvt_pk_bf16_f32 v0, v0, v1
	v_cvt_pk_bf16_f32 v1, v2, v3
	flat_store_dwordx2 v[66:67], v[48:49] offset:16
	v_pk_mul_f32 v[48:49], v[56:57], v[64:65] op_sel_hi:[1,0]
	v_pk_mul_f32 v[50:51], v[58:59], v[64:65] op_sel_hi:[1,0]
	flat_store_dwordx2 v[66:67], v[32:33] offset:80
	v_pk_mul_f32 v[32:33], v[40:41], v[64:65] op_sel_hi:[1,0]
	v_pk_mul_f32 v[34:35], v[42:43], v[64:65] op_sel_hi:[1,0]
	flat_store_dwordx2 v[66:67], v[16:17] offset:144
	v_pk_mul_f32 v[16:17], v[24:25], v[64:65] op_sel_hi:[1,0]
	v_pk_mul_f32 v[18:19], v[26:27], v[64:65] op_sel_hi:[1,0]
	flat_store_dwordx2 v[66:67], v[0:1] offset:208
	v_pk_mul_f32 v[0:1], v[8:9], v[64:65] op_sel_hi:[1,0]
	v_pk_mul_f32 v[2:3], v[10:11], v[64:65] op_sel_hi:[1,0]
	v_cvt_pk_bf16_f32 v48, v48, v49
	v_cvt_pk_bf16_f32 v49, v50, v51
	v_cvt_pk_bf16_f32 v32, v32, v33
	v_cvt_pk_bf16_f32 v33, v34, v35
	v_cvt_pk_bf16_f32 v16, v16, v17
	v_cvt_pk_bf16_f32 v17, v18, v19
	v_cvt_pk_bf16_f32 v0, v0, v1
	v_cvt_pk_bf16_f32 v1, v2, v3
	flat_store_dwordx2 v[66:67], v[48:49] offset:32
	v_pk_mul_f32 v[48:49], v[60:61], v[64:65] op_sel_hi:[1,0]
	v_pk_mul_f32 v[50:51], v[62:63], v[64:65] op_sel_hi:[1,0]
	flat_store_dwordx2 v[66:67], v[32:33] offset:96
	v_pk_mul_f32 v[32:33], v[44:45], v[64:65] op_sel_hi:[1,0]
	v_pk_mul_f32 v[34:35], v[46:47], v[64:65] op_sel_hi:[1,0]
	flat_store_dwordx2 v[66:67], v[16:17] offset:160
	v_pk_mul_f32 v[16:17], v[28:29], v[64:65] op_sel_hi:[1,0]
	v_pk_mul_f32 v[18:19], v[30:31], v[64:65] op_sel_hi:[1,0]
	flat_store_dwordx2 v[66:67], v[0:1] offset:224
	v_pk_mul_f32 v[0:1], v[12:13], v[64:65] op_sel_hi:[1,0]
	v_pk_mul_f32 v[2:3], v[14:15], v[64:65] op_sel_hi:[1,0]
	v_cvt_pk_bf16_f32 v48, v48, v49
	v_cvt_pk_bf16_f32 v49, v50, v51
	v_cvt_pk_bf16_f32 v32, v32, v33
	v_cvt_pk_bf16_f32 v33, v34, v35
	v_cvt_pk_bf16_f32 v16, v16, v17
	v_cvt_pk_bf16_f32 v17, v18, v19
	v_cvt_pk_bf16_f32 v0, v0, v1
	v_cvt_pk_bf16_f32 v1, v2, v3
	flat_store_dwordx2 v[66:67], v[48:49] offset:48
	flat_store_dwordx2 v[66:67], v[32:33] offset:112
	flat_store_dwordx2 v[66:67], v[16:17] offset:176
	flat_store_dwordx2 v[66:67], v[0:1] offset:240
	s_cbranch_scc0 .LBB0_1028

; __device__ __forceinline__ unsigned xb_ld(unsigned* p)              { return __hip_atomic_load(p, __ATOMIC_RELAXED, __HIP_MEMORY_SCOPE_AGENT); }
; __device__ __forceinline__ void xcd_barrier_complete(unsigned* bar, unsigned x, unsigned& nloc, unsigned& nx) {
;     const unsigned G = gridDim.x * gridDim.y * gridDim.z;
;     unsigned sum, cnt, mine, sp = 0u;
;     for (;;) {
;         sum = 0u; cnt = 0u; mine = 0u;
; #pragma unroll
;         for (unsigned j = 0; j < 16; ++j) { const unsigned c = xb_ld(&bar[XB_XCNT(j)]); sum += c; cnt += (c > 0u) ? 1u : 0u; mine = (j == x) ? c : mine; }
; __device__ __forceinline__ void xcd_barrier(const XcdBarrier& b) {
;     asm volatile("s_waitcnt vmcnt(0)" ::: "memory");
;     __syncthreads();
;     if (threadIdx.x == 0) {
;         unsigned* bar = b.bar;
;         __builtin_amdgcn_s_waitcnt(0);
;         unsigned nloc = b.st[0], nx = b.st[1];
;         if (nloc == 0u) { xcd_barrier_complete(bar, b.x, nloc, nx); b.st[0] = nloc; b.st[1] = nx; }
.LBB0_1028:
	s_setprio 0
	s_waitcnt vmcnt(0)
	s_waitcnt vmcnt(0) lgkmcnt(0)
	s_barrier
	s_and_saveexec_b64 s[46:47], s[12:13]
	s_cbranch_execz .LBB0_1072
	s_add_i32 s0, 0, 0x27fc0
	v_mov_b32_e32 v0, s0
	s_waitcnt vmcnt(0) expcnt(0) lgkmcnt(0)
	ds_read_b32 v2, v0
	s_add_i32 s0, 0, 0x27fc4
	v_mov_b32_e32 v0, s0
	ds_read_b32 v0, v0
	s_waitcnt lgkmcnt(1)
	v_cmp_ne_u32_e32 vcc, 0, v2
	s_cbranch_vccnz .LBB0_1043
	v_readlane_b32 s0, v254, 0
	s_mul_i32 s4, s57, s0
	s_add_u32 s0, s54, 0xc00200
	s_addc_u32 s1, s55, 0
	s_add_u32 s8, s54, 0xc00400
	s_addc_u32 s9, s55, 0
	s_add_u32 s10, s54, 0xc00500
	s_addc_u32 s11, s55, 0
	s_add_u32 s16, s54, 0xc00600
	s_addc_u32 s17, s55, 0
	s_add_u32 s18, s54, 0xc00700
	s_addc_u32 s19, s55, 0
	s_add_u32 s20, s54, 0xc00800
	s_addc_u32 s21, s55, 0
	s_add_u32 s22, s54, 0xc00900
	s_addc_u32 s23, s55, 0
	s_add_u32 s24, s54, 0xc00a00
	s_addc_u32 s25, s55, 0
	s_add_u32 s26, s54, 0xc00b00
	s_addc_u32 s27, s55, 0
	s_add_u32 s28, s54, 0xc00c00
	s_addc_u32 s29, s55, 0
	s_add_u32 s30, s54, 0xc00d00
	s_addc_u32 s31, s55, 0
	s_add_u32 s34, s54, 0xc00e00
	s_addc_u32 s35, s55, 0
	s_add_u32 s36, s54, 0xc00f00
	s_addc_u32 s37, s55, 0
	s_add_u32 s38, s54, 0xc01000
	s_addc_u32 s39, s55, 0
	s_add_u32 s50, s54, 0xc01100
	s_addc_u32 s51, s55, 0
	s_add_u32 s58, s54, 0xc01200
	s_addc_u32 s59, s55, 0
	s_add_u32 s60, s54, 0xc01300
	s_addc_u32 s61, s55, 0
	s_mul_i32 s4, s4, s56
	s_mov_b32 s5, 1
	s_mov_b64 s[6:7], 0
	s_waitcnt lgkmcnt(0)
	v_mov_b64_e32 v[0:1], s[8:9]
	v_mov_b64_e32 v[2:3], s[10:11]
	v_mov_b64_e32 v[4:5], s[16:17]
	v_mov_b64_e32 v[6:7], s[18:19]
	v_mov_b64_e32 v[8:9], s[20:21]
	v_mov_b64_e32 v[10:11], s[22:23]
	v_mov_b64_e32 v[12:13], s[24:25]
	v_mov_b64_e32 v[14:15], s[26:27]
	v_mov_b64_e32 v[16:17], s[28:29]
	v_mov_b64_e32 v[18:19], s[30:31]
	v_mov_b64_e32 v[20:21], s[34:35]
	v_mov_b64_e32 v[22:23], s[36:37]
	v_mov_b64_e32 v[24:25], s[38:39]
	v_mov_b64_e32 v[26:27], s[50:51]
	v_mov_b64_e32 v[28:29], s[58:59]
	v_mov_b64_e32 v[30:31], s[60:61]
	s_branch .LBB0_1033
